# weight-conversion schedule rebalanced (fewer tiles in the gate|up GEMM tails that overran, more in the prologue); plus flipped K-loop priorities, saddr DMA
# speedup vs baseline: 1.0060x; 1.0060x over previous
; template <class KA> __device__ __forceinline__ ConvTile conv_desc(KA a, int gidx, int lane) {
;     const int l = gidx / CT_LAYER; int r = gidx - l * CT_LAYER; unsigned char* lw = a->ws + WS_W + (size_t)l * LW_STRIDE;
;     const float* s0; const float* s1 = nullptr; const float* gs = nullptr; bf16* dst; int K, Nsrc, mode = 0, ntn;
;     if (r < CT_GU) { gs = a->in[1] + (size_t)l * DM; s0 = a->in[2] + (size_t)l * DM * DFF; s1 = a->in[3] + (size_t)l * DM * DFF; dst = (bf16*)(lw + LW_GU1); K = DM; Nsrc = DFF; mode = 1; ntn = NGU / 64; }
;     else if ((r -= CT_GU) < CT_D) { s0 = a->in[4] + (size_t)l * DFF * DM; dst = (bf16*)(lw + LW_D1); K = DFF; Nsrc = DM; ntn = DM / 64; }
;     else if ((r -= CT_D) < CT_IN) { gs = a->in[5] + (size_t)l * DM; s0 = a->in[6] + (size_t)l * DM * 15368; dst = (bf16*)(lw + LW_IN); K = DM; Nsrc = 15368; mode = 2; ntn = NZP / 64; }
;     else if ((r -= CT_IN) < CT_LRU) { const int blk = r >> 3; r &= 7; s0 = a->in[12] + ((size_t)l * 8 + blk) * 128 * 128; s1 = a->in[14] + ((size_t)l * 8 + blk) * 128 * 128; dst = (bf16*)(lw + LW_LRU) + (size_t)blk * 256 * 128; K = 128; Nsrc = 128; mode = 3; ntn = 4; }
;     else if ((r -= CT_LRU) < 3 * CT_UP) { const int b = r / CT_UP; r -= b * CT_UP; s0 = (b == 0 ? a->in[17] : (b == 1 ? a->in[18] : a->in[19])) + (size_t)l * 1024 * DM; dst = (bf16*)(lw + LW_UPA + (size_t)b * SZ_WUP); K = 1024; Nsrc = DM; ntn = DM / 64; }
;     else if ((r -= 3 * CT_UP) < CT_OUT) { s0 = a->in[20] + (size_t)l * DM * DM; dst = (bf16*)(lw + LW_OUT); K = DM; Nsrc = DM; ntn = DM / 64; }
;     else if ((r -= CT_OUT) < CT_GU) { gs = a->in[21] + (size_t)l * DM; s0 = a->in[22] + (size_t)l * DM * DFF; s1 = a->in[23] + (size_t)l * DM * DFF; dst = (bf16*)(lw + LW_GU2); K = DM; Nsrc = DFF; mode = 1; ntn = NGU / 64; }
; template <class KA> __device__ __forceinline__ void convert_range(KA a, LAS unsigned char* lds, int t_lo, int t_hi, int rank, int nrank) {
;     int tid_ = threadIdx.x; asm volatile("" : "+v"(tid_));
;     const int lane = tid_ & 63, wave = __builtin_amdgcn_readfirstlane(tid_ >> 6); LAS unsigned short* tl = (LAS unsigned short*)(lds + wave * 16384);
;     const int stride = nrank * 8; int it = t_lo + rank * 8 + wave;
;     if (it >= t_hi) return;
;     f32x4w va[16], vb[16]; float ga[16], gb[16];
;     ConvTile ta = conv_desc(a, it, lane), tb = ta; conv_load(ta, va, ga);
.LBB0_11:
	s_or_b64 exec, exec, s[0:1]
	v_writelane_b32 v250, s8, 4
	s_cmp_eq_u32 s8, 0
	s_nop 0
	v_writelane_b32 v250, s9, 5
	v_writelane_b32 v250, s10, 6
	v_writelane_b32 v250, s11, 7
	s_cbranch_scc1 .LBB0_279
	s_mov_b32 s0, s67
	s_load_dword s40, s[70:71], 0x3f0
	v_mov_b32_e32 v1, v0
	s_add_u32 s2, s70, 0x3f0
	s_addc_u32 s3, s71, 0
	s_lshl_b32 s0, s0, 3
	s_waitcnt lgkmcnt(0)
	s_mov_b32 s28, s40
	s_nop 0
	v_readfirstlane_b32 s24, v1
	s_ashr_i32 s29, s24, 6
	s_add_i32 s41, s29, s0
	s_cmpk_gt_i32 s41, 0x40ff
	s_cbranch_scc1 .LBB0_221
	s_mul_hi_i32 s0, s41, 0x9baade8f
	s_add_i32 s4, s0, s41
	s_load_dwordx2 s[0:1], s[70:71], 0xd8
	s_lshr_b32 s5, s4, 31
	s_ashr_i32 s4, s4, 14
	s_add_i32 s16, s4, s5
	s_mul_i32 s26, s16, 0xffff96c0
	s_add_i32 s26, s26, s41
	s_waitcnt lgkmcnt(0)
	s_add_u32 s42, s0, 0x200000
	s_addc_u32 s43, s1, 0
	s_ashr_i32 s17, s16, 31
	s_mul_i32 s1, s16, 0xd300000
	s_mul_hi_i32 s0, s16, 0xd300000
	s_add_u32 s12, s42, s1
	s_addc_u32 s13, s43, s0
	s_cmpk_gt_i32 s26, 0x157f
	s_cbranch_scc0 .LBB0_21
	s_cmpk_gt_u32 s26, 0x203f
	s_cbranch_scc0 .LBB0_22
	s_cmpk_gt_u32 s26, 0x3ebf
	s_cbranch_scc0 .LBB0_23
	s_cmpk_gt_u32 s26, 0x3eff
	s_cbranch_scc0 .LBB0_24
	s_cmpk_gt_u32 s26, 0x44ff
	s_cbranch_scc0 .LBB0_25
	s_cmpk_gt_u32 s26, 0x48ff
	s_cbranch_scc0 .LBB0_26
	s_cmpk_gt_u32 s26, 0x5e7f
	s_cbranch_scc0 .LBB0_27
	s_load_dwordx2 s[0:1], s[70:71], 0xc0
	s_add_i32 s27, s26, 0xffffa180
	s_mul_i32 s5, s16, 0x2b00000
	s_mul_hi_i32 s4, s16, 0x2b00000
	s_mov_b64 s[6:7], 0
	s_waitcnt lgkmcnt(0)
	s_add_u32 s0, s0, s5
	s_addc_u32 s1, s1, s4
	s_add_u32 s4, s12, 0xbc80000
	s_addc_u32 s5, s13, 0
	s_branch .LBB0_28

; template <class KA> __device__ __forceinline__ ConvTile conv_desc(KA a, int gidx, int lane) {
;     const int l = gidx / CT_LAYER; int r = gidx - l * CT_LAYER; unsigned char* lw = a->ws + WS_W + (size_t)l * LW_STRIDE;
;     const float* s0; const float* s1 = nullptr; const float* gs = nullptr; bf16* dst; int K, Nsrc, mode = 0, ntn;
;     if (r < CT_GU) { gs = a->in[1] + (size_t)l * DM; s0 = a->in[2] + (size_t)l * DM * DFF; s1 = a->in[3] + (size_t)l * DM * DFF; dst = (bf16*)(lw + LW_GU1); K = DM; Nsrc = DFF; mode = 1; ntn = NGU / 64; }
;     else if ((r -= CT_GU) < CT_D) { s0 = a->in[4] + (size_t)l * DFF * DM; dst = (bf16*)(lw + LW_D1); K = DFF; Nsrc = DM; ntn = DM / 64; }
;     else if ((r -= CT_D) < CT_IN) { gs = a->in[5] + (size_t)l * DM; s0 = a->in[6] + (size_t)l * DM * 15368; dst = (bf16*)(lw + LW_IN); K = DM; Nsrc = 15368; mode = 2; ntn = NZP / 64; }
;     else if ((r -= CT_IN) < CT_LRU) { const int blk = r >> 3; r &= 7; s0 = a->in[12] + ((size_t)l * 8 + blk) * 128 * 128; s1 = a->in[14] + ((size_t)l * 8 + blk) * 128 * 128; dst = (bf16*)(lw + LW_LRU) + (size_t)blk * 256 * 128; K = 128; Nsrc = 128; mode = 3; ntn = 4; }
;     else if ((r -= CT_LRU) < 3 * CT_UP) { const int b = r / CT_UP; r -= b * CT_UP; s0 = (b == 0 ? a->in[17] : (b == 1 ? a->in[18] : a->in[19])) + (size_t)l * 1024 * DM; dst = (bf16*)(lw + LW_UPA + (size_t)b * SZ_WUP); K = 1024; Nsrc = DM; ntn = DM / 64; }
;     else if ((r -= 3 * CT_UP) < CT_OUT) { s0 = a->in[20] + (size_t)l * DM * DM; dst = (bf16*)(lw + LW_OUT); K = DM; Nsrc = DM; ntn = DM / 64; }
;     else if ((r -= CT_OUT) < CT_GU) { gs = a->in[21] + (size_t)l * DM; s0 = a->in[22] + (size_t)l * DM * DFF; s1 = a->in[23] + (size_t)l * DM * DFF; dst = (bf16*)(lw + LW_GU2); K = DM; Nsrc = DFF; mode = 1; ntn = NGU / 64; }
;     else { r -= CT_GU; s0 = a->in[24] + (size_t)l * DFF * DM; dst = (bf16*)(lw + LW_D2); K = DFF; Nsrc = DM; ntn = DM / 64; }
; template <class KA> __device__ __forceinline__ void convert_range(KA a, LAS unsigned char* lds, int t_lo, int t_hi, int rank, int nrank) {
;     ...
;     for (;;) {
;         const bool nb = (it + stride) < t_hi; tb = conv_desc(a, nb ? it + stride : it, lane); conv_load(tb, vb, gb);
.LBB0_89:
	s_add_i32 s39, s41, s45
	s_cmpk_lt_i32 s39, 0x4100
	s_cselect_b64 s[10:11], -1, 0
	s_and_b64 s[4:5], s[10:11], exec
	s_cselect_b32 s56, s39, s41
	s_mul_hi_i32 s0, s56, 0x9baade8f
	s_add_i32 s0, s0, s56
	s_lshr_b32 s4, s0, 31
	s_ashr_i32 s0, s0, 14
	s_add_i32 s24, s0, s4
	s_mul_i32 s36, s24, 0xffff96c0
	s_add_i32 s36, s36, s56
	s_ashr_i32 s25, s24, 31
	s_mul_i32 s4, s24, 0xd300000
	s_mul_hi_i32 s0, s24, 0xd300000
	s_add_u32 s22, s42, s4
	s_addc_u32 s23, s43, s0
	s_cmpk_gt_i32 s36, 0x157f
	s_mov_b64 s[34:35], -1
	s_cbranch_scc0 .LBB0_112
	s_cmpk_gt_u32 s36, 0x203f
	s_cbranch_scc0 .LBB0_109
	s_cmpk_gt_u32 s36, 0x3ebf
	s_mov_b64 s[30:31], -1
	s_cbranch_scc0 .LBB0_107
	s_cmpk_gt_u32 s36, 0x3eff
	s_mov_b64 s[28:29], -1
	s_cbranch_scc0 .LBB0_105
	s_cmpk_gt_u32 s36, 0x44ff
	s_cbranch_scc0 .LBB0_102
	s_cmpk_gt_u32 s36, 0x48ff
	s_cbranch_scc0 .LBB0_99
	s_cmpk_gt_u32 s36, 0x5e7f
	s_mov_b64 s[4:5], -1
	s_cbranch_scc0 .LBB0_97
	s_load_dwordx2 s[4:5], s[70:71], 0xc0
	s_add_i32 s37, s36, 0xffffa180
	s_mul_i32 s6, s24, 0x2b00000
	s_mul_hi_i32 s0, s24, 0x2b00000
	s_waitcnt lgkmcnt(0)
	s_add_u32 s12, s4, s6
	s_addc_u32 s13, s5, s0
	s_add_u32 s6, s22, 0xbc80000
	s_addc_u32 s7, s23, 0
	s_mov_b64 s[4:5], 0

; #define LAS __attribute__((address_space(3)))
; __device__ __forceinline__ unsigned pk_bf16(float lo, float hi) { unsigned r; asm volatile("v_cvt_pk_bf16_f32 %0, %1, %2" : "=v"(r) : "v"(lo), "v"(hi)); return r; }
; template <class KA> __device__ __forceinline__ ConvTile conv_desc(KA a, int gidx, int lane) {
;     ...
;     const int n0 = nti * 64, k0 = kti * 64, n = n0 + (lane & 15) * 4; const float* src = s0; int col = n; float sc = 1.f;
;     if (mode == 1) { const int b = (n >> 7) & 1; col = ((n >> 8) << 7) | (n & 127); src = b ? s1 : s0; }
;     else if (mode == 2) { int nl = n; if (n < NZ) { const int p_ = n & 255; nl = (n & ~255) + 64 * ((p_ >> 5) & 3) + 32 * (p_ >> 7) + (p_ & 31); }
;         col = win_src_col(nl); if (nl >= Z_AK && nl < Z_AO) sc = 0.0625f; }
;     else if (mode == 3) { src = (n & 128) ? s1 : s0; col = n & 127; }
;     if (col < 0) { sc = 0.f; col = 0; }
;     ConvTile t; t.sp = src + (size_t)(k0 + (lane >> 4)) * Nsrc + col; t.gs = (gs ? gs : a->in[1]) + k0 % DM + (lane >> 4); t.gm = gs ? 1.f : 0.f; t.dp = dst + (size_t)n0 * K + k0; t.K = K; t.Nsrc = Nsrc; t.sc = sc; return t;
; }
; __device__ __forceinline__ void conv_load(const ConvTile& t, f32x4w (&v)[16], float (&g)[16]) {
; #pragma unroll
;     for (int i = 0; i < 16; ++i) g[i] = t.gs[4 * i];
; #pragma unroll
;     for (int i = 0; i < 16; ++i) v[i] = __builtin_nontemporal_load((const f32x4w*)(t.sp + (size_t)(4 * i) * t.Nsrc));
; }
; __device__ __forceinline__ void conv_finish(const ConvTile& t, const f32x4w (&v)[16], const float (&gg)[16], LAS unsigned short* tl, int lane) {
;     const int nl = (lane & 15) * 4;
; #pragma unroll
;     for (int i = 0; i < 16; ++i) { const float g = (gg[i] * t.gm + (1.f - t.gm)) * t.sc;
;         LAS unsigned* w = (LAS unsigned*)(tl + (4 * i + (lane >> 4)) * 66 + nl); w[0] = pk_bf16(v[i][0] * g, v[i][1] * g); w[1] = pk_bf16(v[i][2] * g, v[i][3] * g); }
.LBB0_151:
	s_lshl_b32 s12, s58, 6
	v_or_b32_e32 v66, s12, v132
	s_ashr_i32 s13, s12, 31
	s_mul_i32 s0, s18, s13
	v_mul_lo_u32 v68, s19, v66
	v_mad_u64_u32 v[66:67], s[20:21], s18, v66, 0
	v_add3_u32 v67, v67, s0, v68
	s_bfe_i32 s0, s58, 0x10019
	s_lshr_b32 s0, s0, 21
	s_add_i32 s0, s12, s0
	s_and_b32 s0, s0, 0xfffff800
	s_sub_i32 s20, s12, s0
	s_ashr_i32 s21, s20, 31
	v_max_i32_e32 v130, 0, v164
	v_lshl_add_u64 v[66:67], v[66:67], 2, s[22:23]
	s_lshl_b64 s[20:21], s[20:21], 2
	v_lshl_add_u64 v[66:67], v[130:131], 2, v[66:67]
	s_waitcnt lgkmcnt(0)
	s_add_u32 s16, s16, s20
	v_sub_f32_e64 v130, 1.0, s38
	s_addc_u32 s17, s17, s21
	s_lshl_b64 s[18:19], s[18:19], 4
	s_waitcnt vmcnt(31)
	v_fma_f32 v68, s38, v143, v130
	v_lshlrev_b32_e32 v182, 2, v132
	v_mul_f32_e32 v137, v163, v68
	v_lshl_add_u64 v[68:69], v[66:67], 0, s[18:19]
	global_load_dword v180, v182, s[16:17]
	global_load_dword v179, v182, s[16:17] offset:16
	global_load_dword v178, v182, s[16:17] offset:32
	global_load_dword v177, v182, s[16:17] offset:48
	global_load_dword v175, v182, s[16:17] offset:64
	global_load_dword v173, v182, s[16:17] offset:80
	global_load_dword v171, v182, s[16:17] offset:96
	global_load_dword v169, v182, s[16:17] offset:112
	global_load_dword v176, v182, s[16:17] offset:128
	global_load_dword v174, v182, s[16:17] offset:144
	global_load_dword v172, v182, s[16:17] offset:160
	global_load_dword v170, v182, s[16:17] offset:176
	global_load_dword v168, v182, s[16:17] offset:192
	global_load_dword v167, v182, s[16:17] offset:208
	global_load_dword v166, v182, s[16:17] offset:224
	global_load_dword v165, v182, s[16:17] offset:240
	global_load_dwordx4 v[126:129], v[66:67], off nt
	v_lshl_add_u64 v[66:67], v[68:69], 0, s[18:19]
	v_lshl_add_u64 v[70:71], v[66:67], 0, s[18:19]
	global_load_dwordx4 v[122:125], v[68:69], off nt
	global_load_dwordx4 v[118:121], v[66:67], off nt
	v_lshl_add_u64 v[66:67], v[70:71], 0, s[18:19]
	v_lshl_add_u64 v[68:69], v[66:67], 0, s[18:19]
	global_load_dwordx4 v[114:117], v[70:71], off nt
	global_load_dwordx4 v[110:113], v[66:67], off nt
	v_lshl_add_u64 v[66:67], v[68:69], 0, s[18:19]
	v_lshl_add_u64 v[70:71], v[66:67], 0, s[18:19]
	global_load_dwordx4 v[106:109], v[68:69], off nt
	global_load_dwordx4 v[102:105], v[66:67], off nt
	v_lshl_add_u64 v[66:67], v[70:71], 0, s[18:19]
	v_lshl_add_u64 v[68:69], v[66:67], 0, s[18:19]
	global_load_dwordx4 v[98:101], v[70:71], off nt
	global_load_dwordx4 v[94:97], v[66:67], off nt
	v_lshl_add_u64 v[66:67], v[68:69], 0, s[18:19]
	global_load_dwordx4 v[90:93], v[68:69], off nt
	v_lshl_add_u64 v[68:69], v[66:67], 0, s[18:19]
	global_load_dwordx4 v[86:89], v[66:67], off nt
	v_lshl_add_u64 v[66:67], v[68:69], 0, s[18:19]
	global_load_dwordx4 v[82:85], v[68:69], off nt
	v_lshl_add_u64 v[68:69], v[66:67], 0, s[18:19]
	global_load_dwordx4 v[78:81], v[66:67], off nt
	v_lshl_add_u64 v[66:67], v[68:69], 0, s[18:19]
	s_waitcnt vmcnt(44)
	v_mul_f32_e32 v183, v2, v137
	global_load_dwordx4 v[74:77], v[68:69], off nt
	v_lshl_add_u64 v[68:69], v[66:67], 0, s[18:19]
	v_mul_f32_e32 v184, v3, v137
	global_load_dwordx4 v[70:73], v[66:67], off nt
	s_nop 0
	global_load_dwordx4 v[66:69], v[68:69], off nt
	v_cvt_pk_bf16_f32 v183, v183, v184
	ds_write_b32 v139, v183
	v_mul_f32_e32 v183, v4, v137
	v_mul_f32_e32 v137, v5, v137
	v_cvt_pk_bf16_f32 v137, v183, v137
	ds_write_b32 v139, v137 offset:4
	v_fma_f32 v137, s38, v145, v130
	v_mul_f32_e32 v137, v163, v137
	s_waitcnt vmcnt(46)
	v_mul_f32_e32 v183, v6, v137
	v_mul_f32_e32 v184, v7, v137
	v_cvt_pk_bf16_f32 v183, v183, v184
	ds_write_b32 v139, v183 offset:528
	v_mul_f32_e32 v183, v8, v137
	v_mul_f32_e32 v137, v9, v137
	v_cvt_pk_bf16_f32 v137, v183, v137
	ds_write_b32 v139, v137 offset:532
	v_fma_f32 v137, s38, v147, v130
	v_mul_f32_e32 v137, v163, v137
	s_waitcnt vmcnt(45)
	v_mul_f32_e32 v183, v10, v137
	v_mul_f32_e32 v184, v11, v137
	v_cvt_pk_bf16_f32 v183, v183, v184
	ds_write_b32 v139, v183 offset:1056
	v_mul_f32_e32 v183, v12, v137
	v_mul_f32_e32 v137, v13, v137
	v_cvt_pk_bf16_f32 v137, v183, v137
	ds_write_b32 v139, v137 offset:1060
	v_fma_f32 v137, s38, v149, v130
	v_mul_f32_e32 v137, v163, v137
	s_waitcnt vmcnt(44)
	v_mul_f32_e32 v183, v14, v137
	v_mul_f32_e32 v184, v15, v137
	v_cvt_pk_bf16_f32 v183, v183, v184
	ds_write_b32 v139, v183 offset:1584
	v_mul_f32_e32 v183, v16, v137
	v_mul_f32_e32 v137, v17, v137
	v_cvt_pk_bf16_f32 v137, v183, v137
	ds_write_b32 v139, v137 offset:1588
	v_fma_f32 v137, s38, v151, v130
	v_mul_f32_e32 v137, v163, v137
	s_waitcnt vmcnt(43)
	v_mul_f32_e32 v183, v18, v137
	v_mul_f32_e32 v184, v19, v137
	v_cvt_pk_bf16_f32 v183, v183, v184
	ds_write_b32 v139, v183 offset:2112
	v_mul_f32_e32 v183, v20, v137
	v_mul_f32_e32 v137, v21, v137
	v_cvt_pk_bf16_f32 v137, v183, v137
	ds_write_b32 v139, v137 offset:2116
	v_fma_f32 v137, s38, v152, v130
	v_mul_f32_e32 v137, v163, v137
	s_waitcnt vmcnt(42)
	v_mul_f32_e32 v183, v22, v137
	v_mul_f32_e32 v184, v23, v137
	v_cvt_pk_bf16_f32 v183, v183, v184
	ds_write_b32 v139, v183 offset:2640
	v_mul_f32_e32 v183, v24, v137
	v_mul_f32_e32 v137, v25, v137
	v_cvt_pk_bf16_f32 v137, v183, v137
	ds_write_b32 v139, v137 offset:2644
	v_fma_f32 v137, s38, v153, v130
	v_mul_f32_e32 v137, v163, v137
	s_waitcnt vmcnt(41)
	v_mul_f32_e32 v183, v26, v137
	v_mul_f32_e32 v184, v27, v137
	v_cvt_pk_bf16_f32 v183, v183, v184
	ds_write_b32 v139, v183 offset:3168
	v_mul_f32_e32 v183, v28, v137
	v_mul_f32_e32 v137, v29, v137
	v_cvt_pk_bf16_f32 v137, v183, v137
	ds_write_b32 v139, v137 offset:3172
	v_fma_f32 v137, s38, v154, v130
	v_mul_f32_e32 v137, v163, v137
	s_waitcnt vmcnt(40)
; #define LAS __attribute__((address_space(3)))
; __device__ __forceinline__ unsigned pk_bf16(float lo, float hi) { unsigned r; asm volatile("v_cvt_pk_bf16_f32 %0, %1, %2" : "=v"(r) : "v"(lo), "v"(hi)); return r; }
; __device__ __forceinline__ void conv_finish(const ConvTile& t, const f32x4w (&v)[16], const float (&gg)[16], LAS unsigned short* tl, int lane) {
;     const int nl = (lane & 15) * 4;
; #pragma unroll
;     for (int i = 0; i < 16; ++i) { const float g = (gg[i] * t.gm + (1.f - t.gm)) * t.sc;
;         LAS unsigned* w = (LAS unsigned*)(tl + (4 * i + (lane >> 4)) * 66 + nl); w[0] = pk_bf16(v[i][0] * g, v[i][1] * g); w[1] = pk_bf16(v[i][2] * g, v[i][3] * g); }
;     asm volatile("s_waitcnt lgkmcnt(0)" ::: "memory");
;     const int kc = (lane & 7) * 8;
; #pragma unroll
;     for (int q = 0; q < 8; ++q) { const int r = 8 * q + (lane >> 3); unsigned w[4];
; #pragma unroll
;         for (int e = 0; e < 4; ++e) w[e] = (unsigned)tl[(kc + 2 * e) * 66 + r] | ((unsigned)tl[(kc + 2 * e + 1) * 66 + r] << 16);
	v_mul_f32_e32 v183, v30, v137
	v_mul_f32_e32 v184, v31, v137
	v_cvt_pk_bf16_f32 v183, v183, v184
	ds_write_b32 v139, v183 offset:3696
	v_mul_f32_e32 v183, v32, v137
	v_mul_f32_e32 v137, v33, v137
	v_cvt_pk_bf16_f32 v137, v183, v137
	ds_write_b32 v139, v137 offset:3700
	v_fma_f32 v137, s38, v155, v130
	v_mul_f32_e32 v137, v163, v137
	s_waitcnt vmcnt(39)
	v_mul_f32_e32 v183, v34, v137
	v_mul_f32_e32 v184, v35, v137
	v_cvt_pk_bf16_f32 v183, v183, v184
	ds_write_b32 v139, v183 offset:4224
	v_mul_f32_e32 v183, v36, v137
	v_mul_f32_e32 v137, v37, v137
	v_cvt_pk_bf16_f32 v137, v183, v137
	ds_write_b32 v139, v137 offset:4228
	v_fma_f32 v137, s38, v156, v130
	v_mul_f32_e32 v137, v163, v137
	s_waitcnt vmcnt(38)
	v_mul_f32_e32 v183, v38, v137
	v_mul_f32_e32 v184, v39, v137
	v_cvt_pk_bf16_f32 v183, v183, v184
	ds_write_b32 v139, v183 offset:4752
	v_mul_f32_e32 v183, v40, v137
	v_mul_f32_e32 v137, v41, v137
	v_cvt_pk_bf16_f32 v137, v183, v137
	ds_write_b32 v139, v137 offset:4756
	v_fma_f32 v137, s38, v157, v130
	v_mul_f32_e32 v137, v163, v137
	s_waitcnt vmcnt(37)
	v_mul_f32_e32 v183, v42, v137
	v_mul_f32_e32 v184, v43, v137
	v_cvt_pk_bf16_f32 v183, v183, v184
	ds_write_b32 v139, v183 offset:5280
	v_mul_f32_e32 v183, v44, v137
	v_mul_f32_e32 v137, v45, v137
	v_cvt_pk_bf16_f32 v137, v183, v137
	ds_write_b32 v139, v137 offset:5284
	v_fma_f32 v137, s38, v158, v130
	v_mul_f32_e32 v137, v163, v137
	s_waitcnt vmcnt(36)
	v_mul_f32_e32 v183, v46, v137
	v_mul_f32_e32 v184, v47, v137
	v_cvt_pk_bf16_f32 v183, v183, v184
	ds_write_b32 v139, v183 offset:5808
	v_mul_f32_e32 v183, v48, v137
	v_mul_f32_e32 v137, v49, v137
	v_cvt_pk_bf16_f32 v137, v183, v137
	ds_write_b32 v139, v137 offset:5812
	v_fma_f32 v137, s38, v159, v130
	v_mul_f32_e32 v137, v163, v137
	s_waitcnt vmcnt(35)
	v_mul_f32_e32 v183, v50, v137
	v_mul_f32_e32 v184, v51, v137
	v_cvt_pk_bf16_f32 v183, v183, v184
	ds_write_b32 v139, v183 offset:6336
	v_mul_f32_e32 v183, v52, v137
	v_mul_f32_e32 v137, v53, v137
	v_cvt_pk_bf16_f32 v137, v183, v137
	ds_write_b32 v139, v137 offset:6340
	v_fma_f32 v137, s38, v160, v130
	v_mul_f32_e32 v137, v163, v137
	s_waitcnt vmcnt(34)
	v_mul_f32_e32 v183, v54, v137
	v_mul_f32_e32 v184, v55, v137
	v_cvt_pk_bf16_f32 v183, v183, v184
	ds_write_b32 v139, v183 offset:6864
	v_mul_f32_e32 v183, v56, v137
	v_mul_f32_e32 v137, v57, v137
	v_cvt_pk_bf16_f32 v137, v183, v137
	ds_write_b32 v139, v137 offset:6868
	v_fma_f32 v137, s38, v161, v130
	v_mul_f32_e32 v137, v163, v137
	s_waitcnt vmcnt(33)
	v_mul_f32_e32 v183, v58, v137
	v_mul_f32_e32 v184, v59, v137
	v_cvt_pk_bf16_f32 v183, v183, v184
	ds_write_b32 v139, v183 offset:7392
	v_mul_f32_e32 v183, v60, v137
	v_mul_f32_e32 v137, v61, v137
	v_fmac_f32_e32 v130, s38, v162
	v_cvt_pk_bf16_f32 v137, v183, v137
	v_mul_f32_e32 v130, v163, v130
	ds_write_b32 v139, v137 offset:7396
	s_waitcnt vmcnt(32)
	v_mul_f32_e32 v137, v62, v130
	v_mul_f32_e32 v183, v63, v130
	v_cvt_pk_bf16_f32 v137, v137, v183
	ds_write_b32 v139, v137 offset:7920
	v_mul_f32_e32 v137, v64, v130
	v_mul_f32_e32 v130, v65, v130
	v_cvt_pk_bf16_f32 v130, v137, v130
	ds_write_b32 v139, v130 offset:7924
	s_waitcnt lgkmcnt(0)
	ds_read_u16 v130, v133
	ds_read_u16 v183, v133 offset:16
	ds_read_u16 v190, v133 offset:32
	ds_read_u16 v191, v133 offset:48
	ds_read_u16 v192, v133 offset:64
	ds_read_u16 v193, v133 offset:80
	ds_read_u16 v194, v133 offset:96
	ds_read_u16 v195, v133 offset:112
	ds_read_u16 v137, v133 offset:132
	ds_read_u16 v196, v133 offset:148
	ds_read_u16 v197, v133 offset:164
	ds_read_u16 v198, v133 offset:180
	ds_read_u16 v199, v133 offset:196
	ds_read_u16 v200, v133 offset:212
	ds_read_u16 v201, v133 offset:228
	ds_read_u16 v202, v133 offset:244
	ds_read_u16 v185, v133 offset:264
	ds_read_u16 v203, v133 offset:280
	ds_read_u16 v204, v133 offset:296
	ds_read_u16 v205, v133 offset:312
	ds_read_u16 v206, v133 offset:328
	ds_read_u16 v207, v133 offset:344
	ds_read_u16 v208, v133 offset:360
	ds_read_u16 v209, v133 offset:376
	ds_read_u16 v186, v133 offset:396
	ds_read_u16 v210, v133 offset:412
	ds_read_u16 v211, v133 offset:428
	ds_read_u16 v212, v133 offset:444
	ds_read_u16 v213, v133 offset:460
	ds_read_u16 v214, v133 offset:476
	ds_read_u16 v215, v133 offset:492
	ds_read_u16 v216, v133 offset:508
	s_waitcnt lgkmcnt(14)
	v_lshl_or_b32 v184, v137, 16, v130
	ds_read_u16 v130, v133 offset:528
	ds_read_u16 v217, v133 offset:544
	ds_read_u16 v218, v133 offset:560
	ds_read_u16 v219, v133 offset:576
	ds_read_u16 v220, v133 offset:592
	ds_read_u16 v221, v133 offset:608
	ds_read_u16 v222, v133 offset:624
	ds_read_u16 v223, v133 offset:640
	ds_read_u16 v137, v133 offset:660
	ds_read_u16 v224, v133 offset:676
	ds_read_u16 v225, v133 offset:692
	ds_read_u16 v226, v133 offset:708
	ds_read_u16 v227, v133 offset:724
	ds_read_u16 v228, v133 offset:740
	ds_read_u16 v229, v133 offset:756
	ds_read_u16 v230, v133 offset:772
	s_waitcnt lgkmcnt(14)
; #define LAS __attribute__((address_space(3)))
; template <class KA> __device__ __forceinline__ ConvTile conv_desc(KA a, int gidx, int lane) {
;     const int l = gidx / CT_LAYER; int r = gidx - l * CT_LAYER; unsigned char* lw = a->ws + WS_W + (size_t)l * LW_STRIDE;
;     const float* s0; const float* s1 = nullptr; const float* gs = nullptr; bf16* dst; int K, Nsrc, mode = 0, ntn;
;     if (r < CT_GU) { gs = a->in[1] + (size_t)l * DM; s0 = a->in[2] + (size_t)l * DM * DFF; s1 = a->in[3] + (size_t)l * DM * DFF; dst = (bf16*)(lw + LW_GU1); K = DM; Nsrc = DFF; mode = 1; ntn = NGU / 64; }
;     else if ((r -= CT_GU) < CT_D) { s0 = a->in[4] + (size_t)l * DFF * DM; dst = (bf16*)(lw + LW_D1); K = DFF; Nsrc = DM; ntn = DM / 64; }
; __device__ __forceinline__ void conv_finish(const ConvTile& t, const f32x4w (&v)[16], const float (&gg)[16], LAS unsigned short* tl, int lane) {
;     ...
;     const int kc = (lane & 7) * 8;
; #pragma unroll
;     for (int q = 0; q < 8; ++q) { const int r = 8 * q + (lane >> 3); unsigned w[4];
; #pragma unroll
;         for (int e = 0; e < 4; ++e) w[e] = (unsigned)tl[(kc + 2 * e) * 66 + r] | ((unsigned)tl[(kc + 2 * e + 1) * 66 + r] << 16);
;         __builtin_nontemporal_store((u32x4w){w[0], w[1], w[2], w[3]}, (u32x4w*)(t.dp + (size_t)r * t.K + kc)); }
;     asm volatile("s_waitcnt lgkmcnt(0)" ::: "memory");
; }
; template <class KA> __device__ __forceinline__ void convert_range(KA a, LAS unsigned char* lds, int t_lo, int t_hi, int rank, int nrank) {
;     int tid_ = threadIdx.x; asm volatile("" : "+v"(tid_));
;     const int lane = tid_ & 63, wave = __builtin_amdgcn_readfirstlane(tid_ >> 6); LAS unsigned short* tl = (LAS unsigned short*)(lds + wave * 16384);
;     const int stride = nrank * 8; int it = t_lo + rank * 8 + wave;
;     if (it >= t_hi) return;
;     f32x4w va[16], vb[16]; float ga[16], gb[16];
;     ConvTile ta = conv_desc(a, it, lane), tb = ta; conv_load(ta, va, ga);
;     for (;;) {
;         const bool nb = (it + stride) < t_hi; tb = conv_desc(a, nb ? it + stride : it, lane); conv_load(tb, vb, gb);
;         conv_finish(ta, va, ga, tl, lane);
;         if (!nb) break;
;         it += stride;
;         const bool na = (it + stride) < t_hi; ta = conv_desc(a, na ? it + stride : it, lane); conv_load(ta, va, ga);
;         conv_finish(tb, vb, gb, tl, lane);
;         if (!na) break;
	v_lshl_or_b32 v185, v186, 16, v185
	s_waitcnt lgkmcnt(7)
	v_lshl_or_b32 v186, v137, 16, v130
	ds_read_u16 v130, v133 offset:792
	ds_read_u16 v231, v133 offset:808
	ds_read_u16 v232, v133 offset:824
	ds_read_u16 v233, v133 offset:840
	ds_read_u16 v234, v133 offset:856
	ds_read_u16 v235, v133 offset:872
	ds_read_u16 v236, v133 offset:888
	ds_read_u16 v237, v133 offset:904
	ds_read_u16 v137, v133 offset:924
	ds_read_u16 v238, v133 offset:940
	ds_read_u16 v239, v133 offset:956
	ds_read_u16 v240, v133 offset:972
	ds_read_u16 v241, v133 offset:988
	ds_read_u16 v242, v133 offset:1004
	ds_read_u16 v243, v133 offset:1020
	ds_read_u16 v244, v133 offset:1036
	v_mad_u64_u32 v[188:189], s[16:17], s44, v134, 0
	s_waitcnt lgkmcnt(7)
	v_lshl_or_b32 v187, v137, 16, v130
	v_lshl_add_u64 v[188:189], v[188:189], 1, s[8:9]
	v_mov_b32_e32 v137, v131
	v_lshl_add_u64 v[188:189], v[188:189], 0, v[136:137]
	global_store_dwordx4 v[188:189], v[184:187], off nt
	v_mad_u64_u32 v[188:189], s[16:17], s44, v138, 0
	v_lshl_add_u64 v[188:189], v[188:189], 1, s[8:9]
	v_lshl_or_b32 v184, v196, 16, v183
	v_lshl_or_b32 v185, v210, 16, v203
	v_lshl_or_b32 v186, v224, 16, v217
	s_waitcnt lgkmcnt(6)
	v_lshl_or_b32 v187, v238, 16, v231
	v_lshl_add_u64 v[188:189], v[188:189], 0, v[136:137]
	global_store_dwordx4 v[188:189], v[184:187], off nt
	v_mad_u64_u32 v[188:189], s[16:17], s44, v140, 0
	v_lshl_add_u64 v[188:189], v[188:189], 1, s[8:9]
	v_lshl_or_b32 v184, v197, 16, v190
	v_lshl_or_b32 v185, v211, 16, v204
	v_lshl_or_b32 v186, v225, 16, v218
	s_waitcnt lgkmcnt(5)
	v_lshl_or_b32 v187, v239, 16, v232
	v_lshl_add_u64 v[188:189], v[188:189], 0, v[136:137]
	global_store_dwordx4 v[188:189], v[184:187], off nt
	v_mad_u64_u32 v[188:189], s[16:17], s44, v142, 0
	v_lshl_add_u64 v[188:189], v[188:189], 1, s[8:9]
	v_lshl_or_b32 v184, v198, 16, v191
	v_lshl_or_b32 v185, v212, 16, v205
	v_lshl_or_b32 v186, v226, 16, v219
	s_waitcnt lgkmcnt(4)
	v_lshl_or_b32 v187, v240, 16, v233
	v_lshl_add_u64 v[188:189], v[188:189], 0, v[136:137]
	global_store_dwordx4 v[188:189], v[184:187], off nt
	v_mad_u64_u32 v[188:189], s[16:17], s44, v144, 0
	v_lshl_add_u64 v[188:189], v[188:189], 1, s[8:9]
	v_lshl_or_b32 v184, v199, 16, v192
	v_lshl_or_b32 v185, v213, 16, v206
	v_lshl_or_b32 v186, v227, 16, v220
	s_waitcnt lgkmcnt(3)
	v_lshl_or_b32 v187, v241, 16, v234
	v_lshl_add_u64 v[188:189], v[188:189], 0, v[136:137]
	global_store_dwordx4 v[188:189], v[184:187], off nt
	v_mad_u64_u32 v[188:189], s[16:17], s44, v146, 0
	v_lshl_add_u64 v[188:189], v[188:189], 1, s[8:9]
	v_lshl_or_b32 v184, v200, 16, v193
	v_lshl_or_b32 v185, v214, 16, v207
	v_lshl_or_b32 v186, v228, 16, v221
	s_waitcnt lgkmcnt(2)
	v_lshl_or_b32 v187, v242, 16, v235
	v_lshl_add_u64 v[188:189], v[188:189], 0, v[136:137]
	global_store_dwordx4 v[188:189], v[184:187], off nt
	v_mad_u64_u32 v[188:189], s[16:17], s44, v148, 0
	v_lshl_add_u64 v[188:189], v[188:189], 1, s[8:9]
	v_lshl_or_b32 v184, v201, 16, v194
	v_lshl_or_b32 v185, v215, 16, v208
	v_lshl_or_b32 v186, v229, 16, v222
	s_waitcnt lgkmcnt(1)
	v_lshl_or_b32 v187, v243, 16, v236
	v_lshl_add_u64 v[188:189], v[188:189], 0, v[136:137]
	global_store_dwordx4 v[188:189], v[184:187], off nt
	v_mad_u64_u32 v[188:189], s[16:17], s44, v150, 0
	v_lshl_add_u64 v[188:189], v[188:189], 1, s[8:9]
	v_lshl_or_b32 v184, v202, 16, v195
	v_lshl_or_b32 v185, v216, 16, v209
	v_lshl_or_b32 v186, v230, 16, v223
	s_waitcnt lgkmcnt(0)
	v_lshl_or_b32 v187, v244, 16, v237
	v_lshl_add_u64 v[188:189], v[188:189], 0, v[136:137]
	global_store_dwordx4 v[188:189], v[184:187], off nt
	s_waitcnt lgkmcnt(0)
	s_andn2_b64 vcc, exec, s[10:11]
	s_mov_b64 s[10:11], 0
	s_cbranch_vccnz .LBB0_88
	s_add_i32 s0, s39, s45
	s_cmpk_lt_i32 s0, 0x4100
	s_cselect_b64 s[10:11], -1, 0
	s_and_b64 s[8:9], s[10:11], exec
	s_cselect_b32 s41, s0, s39
	s_mul_hi_i32 s0, s41, 0x9baade8f
	s_add_i32 s0, s0, s41
	s_lshr_b32 s8, s0, 31
	s_ashr_i32 s0, s0, 14
	s_add_i32 s26, s0, s8
	s_mul_i32 s38, s26, 0xffff96c0
	s_add_i32 s38, s38, s41
	s_ashr_i32 s27, s26, 31
	s_mul_i32 s8, s26, 0xd300000
	s_mul_hi_i32 s0, s26, 0xd300000
	s_add_u32 s24, s42, s8
	s_addc_u32 s25, s43, s0
	s_cmpk_gt_i32 s38, 0x157f
	s_mov_b64 s[36:37], -1
	s_cbranch_scc0 .LBB0_165
	s_cmpk_gt_u32 s38, 0x203f
	s_cbranch_scc0 .LBB0_218
	s_cmpk_gt_u32 s38, 0x3ebf
	s_mov_b64 s[34:35], -1
	s_cbranch_scc0 .LBB0_216
	s_cmpk_gt_u32 s38, 0x3eff
	s_mov_b64 s[30:31], -1
	s_cbranch_scc0 .LBB0_214
	s_cmpk_gt_u32 s38, 0x44ff
	s_cbranch_scc0 .LBB0_211
	s_cmpk_gt_u32 s38, 0x48ff
	s_cbranch_scc0 .LBB0_208
	s_cmpk_gt_u32 s38, 0x5e7f
	s_mov_b64 s[18:19], -1
	s_cbranch_scc0 .LBB0_160
	s_load_dwordx2 s[8:9], s[70:71], 0xc0
	s_add_i32 s39, s38, 0xffffa180
	s_mul_i32 s16, s26, 0x2b00000
	s_mul_hi_i32 s0, s26, 0x2b00000
	s_mov_b64 s[18:19], 0
	s_waitcnt lgkmcnt(0)
	s_add_u32 s16, s8, s16
	s_addc_u32 s17, s9, s0
	s_add_u32 s8, s24, 0xbc80000
	s_addc_u32 s9, s25, 0

; #define KP() ({ KArgs kp_ = kp0; asm volatile("" : "+s"(kp_)); kp_; })
; #define G_ ({ int g__ = (int)gridDim.x; asm volatile("" : "+s"(g__)); g__; })
; #define c_ ({ int c__ = (int)blockIdx.x; asm volatile("" : "+s"(c__)); c__; })
; __global__ void __launch_bounds__(512, 2) mega(MegaArgs a) {
;     ...
;             { const int rem = ((T_SEQ / 256) * (NGU / 256)) % G_, q = 3 * l + (half ? 2 : 0), hi = cvt_slot_hi(q) < CVT_TOTAL ? cvt_slot_hi(q) : CVT_TOTAL;
;               if (!(hf & 2) && rem && c_ >= rem && cvt_slot_lo(q) < hi) { KArgs kq = KP(); convert_range(kq, lds, cvt_slot_lo(q), hi, c_ - rem, G_ - rem); } }
.LBB0_308:
	s_mov_b32 s0, s21
	s_abs_i32 s0, s0
	v_cvt_f32_u32_e32 v1, s0
	s_sub_i32 s1, 0, s0
	v_rcp_iflag_f32_e32 v1, v1
	s_nop 0
	v_mul_f32_e32 v1, 0x4f7ffffe, v1
	v_cvt_u32_f32_e32 v1, v1
	s_nop 0
	v_readfirstlane_b32 s2, v1
	s_mul_i32 s1, s1, s2
	s_mul_hi_u32 s1, s2, s1
	s_add_i32 s2, s2, s1
	s_mul_hi_u32 s1, s2, 0x560
	s_mul_i32 s1, s1, s0
	s_sub_i32 s1, 0x560, s1
	s_sub_i32 s2, s1, s0
	s_cmp_ge_u32 s1, s0
	s_cselect_b32 s1, s2, s1
	s_sub_i32 s2, s1, s0
	s_cmp_ge_u32 s1, s0
	v_readlane_b32 s0, v251, 24
	s_cselect_b32 s44, s2, s1
	s_bitcmp1_b32 s0, 1
	s_cselect_b64 s[0:1], -1, 0
	s_cmp_eq_u32 s44, 0
	s_cselect_b64 s[4:5], -1, 0
	s_or_b64 s[0:1], s[0:1], s[4:5]
	s_and_b64 vcc, exec, s[0:1]
	s_cbranch_vccnz .LBB0_496
	v_readlane_b32 s0, v251, 22
	v_readlane_b32 s1, v251, 23
	s_mul_i32 s0, s0, 3
	s_lshl_b32 s1, s52, 1
	s_add_i32 s1, s1, s0
	s_mul_hi_i32 s0, s1, 0x55555556
	s_lshr_b32 s2, s0, 31
	s_add_i32 s0, s0, s2
	s_mul_i32 s2, s0, 3
	s_sub_i32 s1, s1, s2
	s_cmp_eq_u32 s1, 1
	s_movk_i32 s2, 0x20d0
	s_movk_i32 s4, 0x1ce8
	s_cselect_b32 s2, s2, 0x3db8
	s_cselect_b32 s4, s4, 0x20d0
	s_cmp_lg_u32 s1, 0
	s_mulk_i32 s0, 0x5e88
	s_cselect_b32 s1, s2, 0
	s_add_i32 s2, s0, s1
	s_addk_i32 s2, 0x4100
	s_add_i32 s0, s2, s4
	s_min_i32 s26, s0, 0x1a500
	s_mov_b32 s0, s67
	s_cmp_ge_i32 s0, s44
	s_cselect_b64 s[0:1], -1, 0
	s_cmp_lt_i32 s2, s26
	s_cselect_b64 s[4:5], -1, 0
	s_and_b64 s[0:1], s[0:1], s[4:5]
	s_andn2_b64 vcc, exec, s[0:1]
	s_cbranch_vccnz .LBB0_496
	s_mov_b64 s[0:1], s[70:71]
	s_mov_b32 s4, s67
	s_sub_i32 s4, s4, s44
	s_mov_b32 s45, s21
	v_mov_b32_e32 v1, v0
	s_lshl_b32 s4, s4, 3
	v_readfirstlane_b32 s47, v1
	s_ashr_i32 s46, s47, 6
	s_add_i32 s2, s4, s2
	s_add_i32 s27, s2, s46
	s_cmp_ge_i32 s27, s26
	s_cbranch_scc1 .LBB0_496
	s_mul_hi_i32 s2, s27, 0x9baade8f
	s_add_i32 s2, s2, s27
	s_load_dwordx2 s[4:5], s[0:1], 0xd8
	s_waitcnt lgkmcnt(0)
	s_lshr_b32 s6, s2, 31
	s_ashr_i32 s2, s2, 14
	s_add_i32 s30, s2, s6
	s_mul_i32 s42, s30, 0xffff96c0
	s_add_i32 s42, s42, s27
	s_add_u32 s53, s4, 0x200000
	s_addc_u32 s54, s5, 0
	s_ashr_i32 s31, s30, 31
	s_mul_i32 s4, s30, 0xd300000
	s_mul_hi_i32 s2, s30, 0xd300000
	s_add_u32 s28, s53, s4
	s_addc_u32 s29, s54, s2
	s_cmpk_gt_i32 s42, 0x157f
	s_mov_b64 s[40:41], -1
	s_cbranch_scc0 .LBB0_321
	s_cmpk_gt_u32 s42, 0x203f
	s_cbranch_scc1 .LBB0_313
	s_getpc_b64 s[98:99]

; #define KP() ({ KArgs kp_ = kp0; asm volatile("" : "+s"(kp_)); kp_; })
; #define G_ ({ int g__ = (int)gridDim.x; asm volatile("" : "+s"(g__)); g__; })
; #define c_ ({ int c__ = (int)blockIdx.x; asm volatile("" : "+s"(c__)); c__; })
; __global__ void __launch_bounds__(512, 2) mega(MegaArgs a) {
;     ...
;                 { const int rem = ((T_SEQ / 256) * (NZP / 256)) % G_, q = 3 * l + 1, hi = cvt_slot_hi(q) < CVT_TOTAL ? cvt_slot_hi(q) : CVT_TOTAL;
;                   if (!(hf & 2) && rem && c_ >= rem && cvt_slot_lo(q) < hi) { KArgs kq = KP(); convert_range(kq, lds, cvt_slot_lo(q), hi, c_ - rem, G_ - rem); } }
.LBB0_693:
	s_mov_b32 s0, s21
	s_abs_i32 s0, s0
	v_cvt_f32_u32_e32 v1, s0
	s_sub_i32 s1, 0, s0
	v_rcp_iflag_f32_e32 v1, v1
	s_nop 0
	v_mul_f32_e32 v1, 0x4f7ffffe, v1
	v_cvt_u32_f32_e32 v1, v1
	s_nop 0
	v_readfirstlane_b32 s2, v1
	s_mul_i32 s1, s1, s2
	s_mul_hi_u32 s1, s2, s1
	s_add_i32 s2, s2, s1
	s_mul_hi_u32 s1, s2, 0x7a0
	s_mul_i32 s1, s1, s0
	s_sub_i32 s1, 0x7a0, s1
	s_sub_i32 s2, s1, s0
	s_cmp_ge_u32 s1, s0
	s_cselect_b32 s1, s2, s1
	s_sub_i32 s2, s1, s0
	s_cmp_ge_u32 s1, s0
	v_readlane_b32 s0, v251, 24
	s_cselect_b32 s44, s2, s1
	s_bitcmp1_b32 s0, 1
	s_cselect_b64 s[0:1], -1, 0
	s_cmp_eq_u32 s44, 0
	s_waitcnt lgkmcnt(0)
	s_cselect_b64 s[4:5], -1, 0
	s_or_b64 s[0:1], s[0:1], s[4:5]
	s_and_b64 vcc, exec, s[0:1]
	s_cbranch_vccnz .LBB0_881
	v_readlane_b32 s0, v251, 22
	s_mul_i32 s0, s0, 3
	v_readlane_b32 s1, v251, 23
	s_add_i32 s0, s0, 1
	s_mul_hi_i32 s1, s0, 0x55555556
	s_lshr_b32 s2, s1, 31
	s_add_i32 s1, s1, s2
	s_mul_i32 s2, s1, 3
	s_sub_i32 s0, s0, s2
	s_cmp_eq_u32 s0, 1
	s_movk_i32 s2, 0x20d0
	s_movk_i32 s4, 0x1ce8
	s_cselect_b32 s2, s2, 0x3db8
	s_cselect_b32 s4, s4, 0x20d0
	s_cmp_lg_u32 s0, 0
	s_mul_i32 s0, s1, 0x5e88
	s_cselect_b32 s1, s2, 0
	s_add_i32 s2, s0, s1
	s_addk_i32 s2, 0x4100
	s_add_i32 s0, s2, s4
	s_min_i32 s26, s0, 0x1a500
	s_mov_b32 s0, s67
	s_cmp_ge_i32 s0, s44
	s_cselect_b64 s[0:1], -1, 0
	s_cmp_lt_i32 s2, s26
	s_cselect_b64 s[4:5], -1, 0
	s_and_b64 s[0:1], s[0:1], s[4:5]
	s_andn2_b64 vcc, exec, s[0:1]
	s_cbranch_vccnz .LBB0_881
	s_mov_b64 s[0:1], s[70:71]
	s_mov_b32 s4, s67
	s_sub_i32 s4, s4, s44
	s_mov_b32 s45, s21
	v_mov_b32_e32 v1, v0
	s_lshl_b32 s4, s4, 3
	v_readfirstlane_b32 s47, v1
	s_ashr_i32 s46, s47, 6
	s_add_i32 s2, s4, s2
	s_add_i32 s27, s2, s46
	s_cmp_ge_i32 s27, s26
	s_cbranch_scc1 .LBB0_881
	s_mul_hi_i32 s2, s27, 0x9baade8f
	s_add_i32 s2, s2, s27
	s_load_dwordx2 s[4:5], s[0:1], 0xd8
	s_lshr_b32 s6, s2, 31
	s_ashr_i32 s2, s2, 14
	s_add_i32 s30, s2, s6
	s_mul_i32 s42, s30, 0xffff96c0
	s_add_i32 s42, s42, s27
	s_waitcnt lgkmcnt(0)
	s_add_u32 s52, s4, 0x200000
	s_addc_u32 s53, s5, 0
	s_ashr_i32 s31, s30, 31
	s_mul_i32 s4, s30, 0xd300000
	s_mul_hi_i32 s2, s30, 0xd300000
	s_add_u32 s28, s52, s4
	s_addc_u32 s29, s53, s2
	s_cmpk_gt_i32 s42, 0x157f
	s_mov_b64 s[40:41], -1
	s_cbranch_scc0 .LBB0_706
	s_cmpk_gt_u32 s42, 0x203f
	s_cbranch_scc1 .LBB0_698
	s_getpc_b64 s[98:99]
